# h2_scan: four 16-chunk batches unrolled with two register sets, next batch's loads requested before the current batch is processed, on top of v9
# baseline (speedup 1.0000x reference)
.LBB0_407:
	v_add_co_u32_e32 v6, vcc, 0xfff88000, v4
	v_add_u32_e32 v10, 0xfffff880, v2
	s_nop 0
	v_addc_co_u32_e32 v7, vcc, -1, v5, vcc
	v_ashrrev_i32_e32 v11, 31, v10
	v_lshl_add_u64 v[36:37], v[10:11], 2, s[2:3]
	v_add_co_u32_e32 v10, vcc, 0xfff90000, v4
	v_add_u32_e32 v12, 0xfffff900, v2
	s_nop 0
	v_addc_co_u32_e32 v11, vcc, -1, v5, vcc
	v_ashrrev_i32_e32 v13, 31, v12
	v_lshl_add_u64 v[38:39], v[12:13], 2, s[2:3]
	v_add_co_u32_e32 v12, vcc, 0xfff98000, v4
	v_add_u32_e32 v14, 0xfffff980, v2
	s_nop 0
	v_addc_co_u32_e32 v13, vcc, -1, v5, vcc
	v_ashrrev_i32_e32 v15, 31, v14
	v_lshl_add_u64 v[40:41], v[14:15], 2, s[2:3]
	v_add_co_u32_e32 v14, vcc, 0xfffa0000, v4
	v_add_u32_e32 v16, 0xfffffa00, v2
	s_nop 0
	v_addc_co_u32_e32 v15, vcc, -1, v5, vcc
	v_ashrrev_i32_e32 v17, 31, v16
	v_lshl_add_u64 v[42:43], v[16:17], 2, s[2:3]
	v_add_co_u32_e32 v16, vcc, 0xfffa8000, v4
	v_add_u32_e32 v18, 0xfffffa80, v2
	s_nop 0
	v_addc_co_u32_e32 v17, vcc, -1, v5, vcc
	v_ashrrev_i32_e32 v19, 31, v18
	v_lshl_add_u64 v[44:45], v[18:19], 2, s[2:3]
	v_add_co_u32_e32 v18, vcc, 0xfffb0000, v4
	v_add_u32_e32 v20, 0xfffffb00, v2
	s_nop 0
	v_addc_co_u32_e32 v19, vcc, -1, v5, vcc
	v_ashrrev_i32_e32 v21, 31, v20
	v_lshl_add_u64 v[46:47], v[20:21], 2, s[2:3]
	v_add_co_u32_e32 v20, vcc, 0xfffb8000, v4
	v_add_u32_e32 v22, 0xfffffb80, v2
	s_nop 0
	v_addc_co_u32_e32 v21, vcc, -1, v5, vcc
	v_ashrrev_i32_e32 v23, 31, v22
	v_lshl_add_u64 v[48:49], v[22:23], 2, s[2:3]
	v_add_co_u32_e32 v22, vcc, 0xfffc0000, v4
	v_add_u32_e32 v24, 0xfffffc00, v2
	s_nop 0
	v_addc_co_u32_e32 v23, vcc, -1, v5, vcc
	v_ashrrev_i32_e32 v25, 31, v24
	v_lshl_add_u64 v[50:51], v[24:25], 2, s[2:3]
	v_add_co_u32_e32 v24, vcc, 0xfffc8000, v4
	v_add_u32_e32 v26, 0xfffffc80, v2
	s_nop 0
	v_addc_co_u32_e32 v25, vcc, -1, v5, vcc
	v_ashrrev_i32_e32 v27, 31, v26
	v_lshl_add_u64 v[52:53], v[26:27], 2, s[2:3]
	v_add_co_u32_e32 v28, vcc, 0xfffd0000, v4
	v_add_u32_e32 v26, 0xfffffd00, v2
	s_nop 0
	v_addc_co_u32_e32 v29, vcc, -1, v5, vcc
	v_ashrrev_i32_e32 v27, 31, v26
	v_lshl_add_u64 v[54:55], v[26:27], 2, s[2:3]
	v_add_co_u32_e32 v30, vcc, 0xfffd8000, v4
	v_add_u32_e32 v26, 0xfffffd80, v2
	s_nop 0
	v_addc_co_u32_e32 v31, vcc, -1, v5, vcc
	v_ashrrev_i32_e32 v27, 31, v26
	s_mov_b32 s13, 0xfffe0000
	v_lshl_add_u64 v[56:57], v[26:27], 2, s[2:3]
	v_add_co_u32_e32 v26, vcc, s13, v4
	global_load_dword v1, v[6:7], off
	global_load_dword v35, v[10:11], off
	global_load_dword v79, v[12:13], off
	global_load_dword v81, v[14:15], off
	global_load_dword v82, v[16:17], off
	global_load_dword v83, v[18:19], off
	global_load_dword v84, v[20:21], off
	global_load_dword v85, v[22:23], off
	v_addc_co_u32_e32 v27, vcc, -1, v5, vcc
	s_mov_b32 s13, 0xfffe8000
	global_load_dwordx2 v[36:37], v[36:37], off
	v_add_co_u32_e32 v60, vcc, s13, v4
	s_mov_b32 s13, 0xffff0000
	s_nop 0
	v_addc_co_u32_e32 v61, vcc, -1, v5, vcc
	global_load_dword v86, v[24:25], off
	global_load_dword v87, v[28:29], off
	global_load_dword v88, v[30:31], off
	global_load_dword v89, v[26:27], off
	s_nop 0
	global_load_dwordx2 v[38:39], v[38:39], off
	s_nop 0
	global_load_dwordx2 v[40:41], v[40:41], off
	v_add_co_u32_e32 v64, vcc, s13, v4
	v_add_u32_e32 v58, 0xfffffe00, v2
	global_load_dwordx2 v[42:43], v[42:43], off
	v_add_u32_e32 v62, 0xfffffe80, v2
	v_addc_co_u32_e32 v65, vcc, -1, v5, vcc
	v_add_u32_e32 v66, 0xffffff00, v2
	s_movk_i32 s13, 0x8000
	v_add_u32_e32 v70, 0xffffff80, v2
	v_ashrrev_i32_e32 v59, 31, v58
	v_ashrrev_i32_e32 v63, 31, v62
	global_load_dwordx2 v[44:45], v[44:45], off
	v_ashrrev_i32_e32 v67, 31, v66
	v_add_co_u32_e32 v68, vcc, s13, v4
	v_ashrrev_i32_e32 v71, 31, v70
	v_ashrrev_i32_e32 v3, 31, v2
	v_lshl_add_u64 v[58:59], v[58:59], 2, s[2:3]
	v_lshl_add_u64 v[62:63], v[62:63], 2, s[2:3]
	global_load_dwordx2 v[46:47], v[46:47], off
	v_lshl_add_u64 v[66:67], v[66:67], 2, s[2:3]
	v_addc_co_u32_e32 v69, vcc, -1, v5, vcc
	v_lshl_add_u64 v[70:71], v[70:71], 2, s[2:3]
	s_waitcnt vmcnt(23)
	v_lshl_add_u64 v[72:73], v[2:3], 2, s[2:3]
	global_load_dword v90, v[60:61], off
	global_load_dword v91, v[64:65], off
	s_nop 0
	global_load_dwordx2 v[48:49], v[48:49], off
	s_nop 0
	global_load_dwordx2 v[50:51], v[50:51], off
	s_nop 0
	global_load_dwordx2 v[52:53], v[52:53], off
	s_nop 0
	global_load_dwordx2 v[54:55], v[54:55], off
	global_load_dword v92, v[68:69], off
	global_load_dword v93, v[4:5], off
	s_nop 0
	global_load_dwordx2 v[56:57], v[56:57], off
	s_nop 0
	global_load_dwordx2 v[58:59], v[58:59], off
	s_nop 0
	global_load_dwordx2 v[62:63], v[62:63], off
	s_nop 0
	global_load_dwordx2 v[66:67], v[66:67], off
	s_nop 0
	global_load_dwordx2 v[70:71], v[70:71], off
	s_nop 0
	global_load_dwordx2 v[72:73], v[72:73], off
	v_add_u32_e32 v98, 0x800, v2
	v_lshl_add_u64 v[100:101], v[4:5], 0, s[14:15]
	v_add_co_u32_e32 v102, vcc, 0xfff88000, v100
	v_add_u32_e32 v106, 0xfffff880, v98
	s_nop 0
	v_addc_co_u32_e32 v103, vcc, -1, v101, vcc
	v_ashrrev_i32_e32 v107, 31, v106
	v_lshl_add_u64 v[132:133], v[106:107], 2, s[2:3]
	v_add_co_u32_e32 v106, vcc, 0xfff90000, v100
	v_add_u32_e32 v108, 0xfffff900, v98
	s_nop 0
	v_addc_co_u32_e32 v107, vcc, -1, v101, vcc
	v_ashrrev_i32_e32 v109, 31, v108
	v_lshl_add_u64 v[134:135], v[108:109], 2, s[2:3]
	v_add_co_u32_e32 v108, vcc, 0xfff98000, v100
	v_add_u32_e32 v110, 0xfffff980, v98
	s_nop 0
	v_addc_co_u32_e32 v109, vcc, -1, v101, vcc
	v_ashrrev_i32_e32 v111, 31, v110
	v_lshl_add_u64 v[136:137], v[110:111], 2, s[2:3]
	v_add_co_u32_e32 v110, vcc, 0xfffa0000, v100
	v_add_u32_e32 v112, 0xfffffa00, v98
	s_nop 0
	v_addc_co_u32_e32 v111, vcc, -1, v101, vcc
	v_ashrrev_i32_e32 v113, 31, v112
	v_lshl_add_u64 v[138:139], v[112:113], 2, s[2:3]
	v_add_co_u32_e32 v112, vcc, 0xfffa8000, v100
	v_add_u32_e32 v114, 0xfffffa80, v98
	s_nop 0
	v_addc_co_u32_e32 v113, vcc, -1, v101, vcc
	v_ashrrev_i32_e32 v115, 31, v114
	v_lshl_add_u64 v[140:141], v[114:115], 2, s[2:3]
	v_add_co_u32_e32 v114, vcc, 0xfffb0000, v100
	v_add_u32_e32 v116, 0xfffffb00, v98
	s_nop 0
	v_addc_co_u32_e32 v115, vcc, -1, v101, vcc
	v_ashrrev_i32_e32 v117, 31, v116
	v_lshl_add_u64 v[142:143], v[116:117], 2, s[2:3]
	v_add_co_u32_e32 v116, vcc, 0xfffb8000, v100
	v_add_u32_e32 v118, 0xfffffb80, v98
	s_nop 0
	v_addc_co_u32_e32 v117, vcc, -1, v101, vcc
	v_ashrrev_i32_e32 v119, 31, v118
	v_lshl_add_u64 v[144:145], v[118:119], 2, s[2:3]
	v_add_co_u32_e32 v118, vcc, 0xfffc0000, v100
	v_add_u32_e32 v120, 0xfffffc00, v98
	s_nop 0
	v_addc_co_u32_e32 v119, vcc, -1, v101, vcc
	v_ashrrev_i32_e32 v121, 31, v120
	v_lshl_add_u64 v[146:147], v[120:121], 2, s[2:3]
	v_add_co_u32_e32 v120, vcc, 0xfffc8000, v100
	v_add_u32_e32 v122, 0xfffffc80, v98
	s_nop 0
	v_addc_co_u32_e32 v121, vcc, -1, v101, vcc
	v_ashrrev_i32_e32 v123, 31, v122
	v_lshl_add_u64 v[148:149], v[122:123], 2, s[2:3]
	v_add_co_u32_e32 v124, vcc, 0xfffd0000, v100
	v_add_u32_e32 v122, 0xfffffd00, v98
	s_nop 0
	v_addc_co_u32_e32 v125, vcc, -1, v101, vcc
	v_ashrrev_i32_e32 v123, 31, v122
	v_lshl_add_u64 v[150:151], v[122:123], 2, s[2:3]
	v_add_co_u32_e32 v126, vcc, 0xfffd8000, v100
	v_add_u32_e32 v122, 0xfffffd80, v98
	s_nop 0
	v_addc_co_u32_e32 v127, vcc, -1, v101, vcc
	v_ashrrev_i32_e32 v123, 31, v122
	s_mov_b32 s13, 0xfffe0000
	v_lshl_add_u64 v[152:153], v[122:123], 2, s[2:3]
	v_add_co_u32_e32 v122, vcc, s13, v100
	global_load_dword v97, v[102:103], off
	global_load_dword v131, v[106:107], off
	global_load_dword v175, v[108:109], off
	global_load_dword v177, v[110:111], off
	global_load_dword v178, v[112:113], off
	global_load_dword v179, v[114:115], off
	global_load_dword v180, v[116:117], off
	global_load_dword v181, v[118:119], off
	v_addc_co_u32_e32 v123, vcc, -1, v101, vcc
	s_mov_b32 s13, 0xfffe8000
	global_load_dwordx2 v[132:133], v[132:133], off
	v_add_co_u32_e32 v156, vcc, s13, v100
	s_mov_b32 s13, 0xffff0000
	s_nop 0
	v_addc_co_u32_e32 v157, vcc, -1, v101, vcc
	global_load_dword v182, v[120:121], off
	global_load_dword v183, v[124:125], off
	global_load_dword v184, v[126:127], off
	global_load_dword v185, v[122:123], off
	s_nop 0
	global_load_dwordx2 v[134:135], v[134:135], off
	s_nop 0
	global_load_dwordx2 v[136:137], v[136:137], off
	v_add_co_u32_e32 v160, vcc, s13, v100
	v_add_u32_e32 v154, 0xfffffe00, v98
	global_load_dwordx2 v[138:139], v[138:139], off
	v_add_u32_e32 v158, 0xfffffe80, v98
	v_addc_co_u32_e32 v161, vcc, -1, v101, vcc
	v_add_u32_e32 v162, 0xffffff00, v98
	s_movk_i32 s13, 0x8000
	v_add_u32_e32 v166, 0xffffff80, v98
	v_ashrrev_i32_e32 v155, 31, v154
	v_ashrrev_i32_e32 v159, 31, v158
	global_load_dwordx2 v[140:141], v[140:141], off
	v_ashrrev_i32_e32 v163, 31, v162
	v_add_co_u32_e32 v164, vcc, s13, v100
	v_ashrrev_i32_e32 v167, 31, v166
	v_ashrrev_i32_e32 v99, 31, v98
	v_lshl_add_u64 v[154:155], v[154:155], 2, s[2:3]
	v_lshl_add_u64 v[158:159], v[158:159], 2, s[2:3]
	global_load_dwordx2 v[142:143], v[142:143], off
	v_lshl_add_u64 v[162:163], v[162:163], 2, s[2:3]
	v_addc_co_u32_e32 v165, vcc, -1, v101, vcc
	v_lshl_add_u64 v[166:167], v[166:167], 2, s[2:3]
	s_waitcnt vmcnt(23)
	v_lshl_add_u64 v[168:169], v[98:99], 2, s[2:3]
	global_load_dword v186, v[156:157], off
	global_load_dword v187, v[160:161], off
	s_nop 0
	global_load_dwordx2 v[144:145], v[144:145], off
	s_nop 0
	global_load_dwordx2 v[146:147], v[146:147], off
	s_nop 0
	global_load_dwordx2 v[148:149], v[148:149], off
	s_nop 0
	global_load_dwordx2 v[150:151], v[150:151], off
	global_load_dword v188, v[164:165], off
	global_load_dword v189, v[100:101], off
	s_nop 0
	global_load_dwordx2 v[152:153], v[152:153], off
	s_nop 0
	global_load_dwordx2 v[154:155], v[154:155], off
	s_nop 0
	global_load_dwordx2 v[158:159], v[158:159], off
	s_nop 0
	global_load_dwordx2 v[162:163], v[162:163], off
	s_nop 0
	global_load_dwordx2 v[166:167], v[166:167], off
	s_nop 0
	global_load_dwordx2 v[168:169], v[168:169], off
	v_cvt_pk_bf16_f32 v3, v8, v9
	s_waitcnt vmcnt(63)
	v_lshlrev_b32_e32 v74, 16, v1
	v_and_b32_e32 v75, 0xffff0000, v1
	s_waitcnt vmcnt(62)
	v_lshlrev_b32_e32 v76, 16, v35
	v_and_b32_e32 v77, 0xffff0000, v35
	s_waitcnt vmcnt(61)
	v_lshlrev_b32_e32 v78, 16, v79
	v_and_b32_e32 v79, 0xffff0000, v79
	s_waitcnt vmcnt(60)
	v_lshlrev_b32_e32 v80, 16, v81
	v_and_b32_e32 v81, 0xffff0000, v81
	s_waitcnt vmcnt(55)
	v_pk_fma_f32 v[8:9], v[8:9], v[36:37], v[74:75]
	s_nop 0
	v_cvt_pk_bf16_f32 v1, v8, v9
	v_lshlrev_b32_e32 v36, 16, v82
	v_and_b32_e32 v37, 0xffff0000, v82
	s_waitcnt vmcnt(54)
	v_lshlrev_b32_e32 v74, 16, v86
	v_and_b32_e32 v75, 0xffff0000, v86
	s_waitcnt vmcnt(50)
	v_pk_fma_f32 v[8:9], v[8:9], v[38:39], v[76:77]
	s_nop 0
	v_cvt_pk_bf16_f32 v35, v8, v9
	s_waitcnt vmcnt(49)
	v_pk_fma_f32 v[8:9], v[8:9], v[40:41], v[78:79]
	v_lshlrev_b32_e32 v38, 16, v83
	v_cvt_pk_bf16_f32 v78, v8, v9
	s_waitcnt vmcnt(48)
	v_pk_fma_f32 v[8:9], v[8:9], v[42:43], v[80:81]
	v_and_b32_e32 v39, 0xffff0000, v83
	v_cvt_pk_bf16_f32 v79, v8, v9
	v_lshlrev_b32_e32 v40, 16, v84
	v_and_b32_e32 v41, 0xffff0000, v84
	v_lshlrev_b32_e32 v42, 16, v85
	v_and_b32_e32 v43, 0xffff0000, v85
	v_lshlrev_b32_e32 v76, 16, v87
	v_and_b32_e32 v77, 0xffff0000, v87
	s_waitcnt vmcnt(47)
	v_pk_fma_f32 v[8:9], v[8:9], v[44:45], v[36:37]
	v_lshlrev_b32_e32 v36, 16, v88
	v_cvt_pk_bf16_f32 v80, v8, v9
	v_and_b32_e32 v37, 0xffff0000, v88
	s_waitcnt vmcnt(46)
	v_pk_fma_f32 v[8:9], v[8:9], v[46:47], v[38:39]
	s_nop 0
	v_cvt_pk_bf16_f32 v81, v8, v9
	v_lshlrev_b32_e32 v38, 16, v89
	v_and_b32_e32 v39, 0xffff0000, v89
	s_waitcnt vmcnt(43)
	v_pk_fma_f32 v[8:9], v[8:9], v[48:49], v[40:41]
	s_nop 0
	v_cvt_pk_bf16_f32 v48, v8, v9
	s_waitcnt vmcnt(42)
	v_pk_fma_f32 v[8:9], v[8:9], v[50:51], v[42:43]
	v_lshlrev_b32_e32 v40, 16, v90
	v_cvt_pk_bf16_f32 v49, v8, v9
	s_waitcnt vmcnt(41)
	v_pk_fma_f32 v[8:9], v[8:9], v[52:53], v[74:75]
	v_and_b32_e32 v41, 0xffff0000, v90
	v_cvt_pk_bf16_f32 v50, v8, v9
	s_waitcnt vmcnt(40)
	v_pk_fma_f32 v[8:9], v[8:9], v[54:55], v[76:77]
	v_lshlrev_b32_e32 v42, 16, v91
	v_cvt_pk_bf16_f32 v51, v8, v9
	v_and_b32_e32 v43, 0xffff0000, v91
	s_waitcnt vmcnt(39)
	v_lshlrev_b32_e32 v44, 16, v92
	v_and_b32_e32 v45, 0xffff0000, v92
	s_waitcnt vmcnt(38)
	v_lshlrev_b32_e32 v46, 16, v93
	v_and_b32_e32 v47, 0xffff0000, v93
	global_store_dword v[6:7], v3, off
	global_store_dword v[10:11], v1, off
	global_store_dword v[12:13], v35, off
	global_store_dword v[14:15], v78, off
	global_store_dword v[16:17], v79, off
	global_store_dword v[18:19], v80, off
	global_store_dword v[20:21], v81, off
	global_store_dword v[22:23], v48, off
	global_store_dword v[24:25], v49, off
	global_store_dword v[28:29], v50, off
	global_store_dword v[30:31], v51, off
	s_waitcnt vmcnt(48)
	v_pk_fma_f32 v[6:7], v[8:9], v[56:57], v[36:37]
	v_cvt_pk_bf16_f32 v1, v6, v7
	s_waitcnt vmcnt(47)
	v_pk_fma_f32 v[6:7], v[6:7], v[58:59], v[38:39]
	global_store_dword v[26:27], v1, off
	v_cvt_pk_bf16_f32 v1, v6, v7
	s_waitcnt vmcnt(47)
	v_pk_fma_f32 v[6:7], v[6:7], v[62:63], v[40:41]
	global_store_dword v[60:61], v1, off
	v_cvt_pk_bf16_f32 v1, v6, v7
	s_waitcnt vmcnt(47)
	v_pk_fma_f32 v[6:7], v[6:7], v[66:67], v[42:43]
	global_store_dword v[64:65], v1, off
	v_cvt_pk_bf16_f32 v1, v6, v7
	s_waitcnt vmcnt(47)
	v_pk_fma_f32 v[6:7], v[6:7], v[70:71], v[44:45]
	global_store_dword v[68:69], v1, off
	v_cvt_pk_bf16_f32 v1, v6, v7
	s_waitcnt vmcnt(47)
	v_pk_fma_f32 v[8:9], v[6:7], v[72:73], v[46:47]
	global_store_dword v[4:5], v1, off
	v_add_u32_e32 v2, 0x800, v98
	v_lshl_add_u64 v[4:5], v[100:101], 0, s[14:15]
	v_add_co_u32_e32 v6, vcc, 0xfff88000, v4
	v_add_u32_e32 v10, 0xfffff880, v2
	s_nop 0
	v_addc_co_u32_e32 v7, vcc, -1, v5, vcc
	v_ashrrev_i32_e32 v11, 31, v10
	v_lshl_add_u64 v[36:37], v[10:11], 2, s[2:3]
	v_add_co_u32_e32 v10, vcc, 0xfff90000, v4
	v_add_u32_e32 v12, 0xfffff900, v2
	s_nop 0
	v_addc_co_u32_e32 v11, vcc, -1, v5, vcc
	v_ashrrev_i32_e32 v13, 31, v12
	v_lshl_add_u64 v[38:39], v[12:13], 2, s[2:3]
	v_add_co_u32_e32 v12, vcc, 0xfff98000, v4
	v_add_u32_e32 v14, 0xfffff980, v2
	s_nop 0
	v_addc_co_u32_e32 v13, vcc, -1, v5, vcc
	v_ashrrev_i32_e32 v15, 31, v14
	v_lshl_add_u64 v[40:41], v[14:15], 2, s[2:3]
	v_add_co_u32_e32 v14, vcc, 0xfffa0000, v4
	v_add_u32_e32 v16, 0xfffffa00, v2
	s_nop 0
	v_addc_co_u32_e32 v15, vcc, -1, v5, vcc
	v_ashrrev_i32_e32 v17, 31, v16
	v_lshl_add_u64 v[42:43], v[16:17], 2, s[2:3]
	v_add_co_u32_e32 v16, vcc, 0xfffa8000, v4
	v_add_u32_e32 v18, 0xfffffa80, v2
	s_nop 0
	v_addc_co_u32_e32 v17, vcc, -1, v5, vcc
	v_ashrrev_i32_e32 v19, 31, v18
	v_lshl_add_u64 v[44:45], v[18:19], 2, s[2:3]
	v_add_co_u32_e32 v18, vcc, 0xfffb0000, v4
	v_add_u32_e32 v20, 0xfffffb00, v2
	s_nop 0
	v_addc_co_u32_e32 v19, vcc, -1, v5, vcc
	v_ashrrev_i32_e32 v21, 31, v20
	v_lshl_add_u64 v[46:47], v[20:21], 2, s[2:3]
	v_add_co_u32_e32 v20, vcc, 0xfffb8000, v4
	v_add_u32_e32 v22, 0xfffffb80, v2
	s_nop 0
	v_addc_co_u32_e32 v21, vcc, -1, v5, vcc
	v_ashrrev_i32_e32 v23, 31, v22
	v_lshl_add_u64 v[48:49], v[22:23], 2, s[2:3]
	v_add_co_u32_e32 v22, vcc, 0xfffc0000, v4
	v_add_u32_e32 v24, 0xfffffc00, v2
	s_nop 0
	v_addc_co_u32_e32 v23, vcc, -1, v5, vcc
	v_ashrrev_i32_e32 v25, 31, v24
	v_lshl_add_u64 v[50:51], v[24:25], 2, s[2:3]
	v_add_co_u32_e32 v24, vcc, 0xfffc8000, v4
	v_add_u32_e32 v26, 0xfffffc80, v2
	s_nop 0
	v_addc_co_u32_e32 v25, vcc, -1, v5, vcc
	v_ashrrev_i32_e32 v27, 31, v26
	v_lshl_add_u64 v[52:53], v[26:27], 2, s[2:3]
	v_add_co_u32_e32 v28, vcc, 0xfffd0000, v4
	v_add_u32_e32 v26, 0xfffffd00, v2
	s_nop 0
	v_addc_co_u32_e32 v29, vcc, -1, v5, vcc
	v_ashrrev_i32_e32 v27, 31, v26
	v_lshl_add_u64 v[54:55], v[26:27], 2, s[2:3]
	v_add_co_u32_e32 v30, vcc, 0xfffd8000, v4
	v_add_u32_e32 v26, 0xfffffd80, v2
	s_nop 0
	v_addc_co_u32_e32 v31, vcc, -1, v5, vcc
	v_ashrrev_i32_e32 v27, 31, v26
	s_mov_b32 s13, 0xfffe0000
	v_lshl_add_u64 v[56:57], v[26:27], 2, s[2:3]
	v_add_co_u32_e32 v26, vcc, s13, v4
	global_load_dword v1, v[6:7], off
	global_load_dword v35, v[10:11], off
	global_load_dword v79, v[12:13], off
	global_load_dword v81, v[14:15], off
	global_load_dword v82, v[16:17], off
	global_load_dword v83, v[18:19], off
	global_load_dword v84, v[20:21], off
	global_load_dword v85, v[22:23], off
	v_addc_co_u32_e32 v27, vcc, -1, v5, vcc
	s_mov_b32 s13, 0xfffe8000
	global_load_dwordx2 v[36:37], v[36:37], off
	v_add_co_u32_e32 v60, vcc, s13, v4
	s_mov_b32 s13, 0xffff0000
	s_nop 0
	v_addc_co_u32_e32 v61, vcc, -1, v5, vcc
	global_load_dword v86, v[24:25], off
	global_load_dword v87, v[28:29], off
	global_load_dword v88, v[30:31], off
	global_load_dword v89, v[26:27], off
	s_nop 0
	global_load_dwordx2 v[38:39], v[38:39], off
	s_nop 0
	global_load_dwordx2 v[40:41], v[40:41], off
	v_add_co_u32_e32 v64, vcc, s13, v4
	v_add_u32_e32 v58, 0xfffffe00, v2
	global_load_dwordx2 v[42:43], v[42:43], off
	v_add_u32_e32 v62, 0xfffffe80, v2
	v_addc_co_u32_e32 v65, vcc, -1, v5, vcc
	v_add_u32_e32 v66, 0xffffff00, v2
	s_movk_i32 s13, 0x8000
	v_add_u32_e32 v70, 0xffffff80, v2
	v_ashrrev_i32_e32 v59, 31, v58
	v_ashrrev_i32_e32 v63, 31, v62
	global_load_dwordx2 v[44:45], v[44:45], off
	v_ashrrev_i32_e32 v67, 31, v66
	v_add_co_u32_e32 v68, vcc, s13, v4
	v_ashrrev_i32_e32 v71, 31, v70
	v_ashrrev_i32_e32 v3, 31, v2
	v_lshl_add_u64 v[58:59], v[58:59], 2, s[2:3]
	v_lshl_add_u64 v[62:63], v[62:63], 2, s[2:3]
	global_load_dwordx2 v[46:47], v[46:47], off
	v_lshl_add_u64 v[66:67], v[66:67], 2, s[2:3]
	v_addc_co_u32_e32 v69, vcc, -1, v5, vcc
	v_lshl_add_u64 v[70:71], v[70:71], 2, s[2:3]
	s_waitcnt vmcnt(23)
	v_lshl_add_u64 v[72:73], v[2:3], 2, s[2:3]
	global_load_dword v90, v[60:61], off
	global_load_dword v91, v[64:65], off
	s_nop 0
	global_load_dwordx2 v[48:49], v[48:49], off
	s_nop 0
	global_load_dwordx2 v[50:51], v[50:51], off
	s_nop 0
	global_load_dwordx2 v[52:53], v[52:53], off
	s_nop 0
	global_load_dwordx2 v[54:55], v[54:55], off
	global_load_dword v92, v[68:69], off
	global_load_dword v93, v[4:5], off
	s_nop 0
	global_load_dwordx2 v[56:57], v[56:57], off
	s_nop 0
	global_load_dwordx2 v[58:59], v[58:59], off
	s_nop 0
	global_load_dwordx2 v[62:63], v[62:63], off
	s_nop 0
	global_load_dwordx2 v[66:67], v[66:67], off
	s_nop 0
	global_load_dwordx2 v[70:71], v[70:71], off
	s_nop 0
	global_load_dwordx2 v[72:73], v[72:73], off
	v_cvt_pk_bf16_f32 v99, v8, v9
	s_waitcnt vmcnt(63)
	v_lshlrev_b32_e32 v170, 16, v97
	v_and_b32_e32 v171, 0xffff0000, v97
	s_waitcnt vmcnt(62)
	v_lshlrev_b32_e32 v172, 16, v131
	v_and_b32_e32 v173, 0xffff0000, v131
	s_waitcnt vmcnt(61)
	v_lshlrev_b32_e32 v174, 16, v175
	v_and_b32_e32 v175, 0xffff0000, v175
	s_waitcnt vmcnt(60)
	v_lshlrev_b32_e32 v176, 16, v177
	v_and_b32_e32 v177, 0xffff0000, v177
	s_waitcnt vmcnt(55)
	v_pk_fma_f32 v[8:9], v[8:9], v[132:133], v[170:171]
	s_nop 0
	v_cvt_pk_bf16_f32 v97, v8, v9
	v_lshlrev_b32_e32 v132, 16, v178
	v_and_b32_e32 v133, 0xffff0000, v178
	s_waitcnt vmcnt(54)
	v_lshlrev_b32_e32 v170, 16, v182
	v_and_b32_e32 v171, 0xffff0000, v182
	s_waitcnt vmcnt(50)
	v_pk_fma_f32 v[8:9], v[8:9], v[134:135], v[172:173]
	s_nop 0
	v_cvt_pk_bf16_f32 v131, v8, v9
	s_waitcnt vmcnt(49)
	v_pk_fma_f32 v[8:9], v[8:9], v[136:137], v[174:175]
	v_lshlrev_b32_e32 v134, 16, v179
	v_cvt_pk_bf16_f32 v174, v8, v9
	s_waitcnt vmcnt(48)
	v_pk_fma_f32 v[8:9], v[8:9], v[138:139], v[176:177]
	v_and_b32_e32 v135, 0xffff0000, v179
	v_cvt_pk_bf16_f32 v175, v8, v9
	v_lshlrev_b32_e32 v136, 16, v180
	v_and_b32_e32 v137, 0xffff0000, v180
	v_lshlrev_b32_e32 v138, 16, v181
	v_and_b32_e32 v139, 0xffff0000, v181
	v_lshlrev_b32_e32 v172, 16, v183
	v_and_b32_e32 v173, 0xffff0000, v183
	s_waitcnt vmcnt(47)
	v_pk_fma_f32 v[8:9], v[8:9], v[140:141], v[132:133]
	v_lshlrev_b32_e32 v132, 16, v184
	v_cvt_pk_bf16_f32 v176, v8, v9
	v_and_b32_e32 v133, 0xffff0000, v184
	s_waitcnt vmcnt(46)
	v_pk_fma_f32 v[8:9], v[8:9], v[142:143], v[134:135]
	s_nop 0
	v_cvt_pk_bf16_f32 v177, v8, v9
	v_lshlrev_b32_e32 v134, 16, v185
	v_and_b32_e32 v135, 0xffff0000, v185
	s_waitcnt vmcnt(43)
	v_pk_fma_f32 v[8:9], v[8:9], v[144:145], v[136:137]
	s_nop 0
	v_cvt_pk_bf16_f32 v144, v8, v9
	s_waitcnt vmcnt(42)
	v_pk_fma_f32 v[8:9], v[8:9], v[146:147], v[138:139]
	v_lshlrev_b32_e32 v136, 16, v186
	v_cvt_pk_bf16_f32 v145, v8, v9
	s_waitcnt vmcnt(41)
	v_pk_fma_f32 v[8:9], v[8:9], v[148:149], v[170:171]
	v_and_b32_e32 v137, 0xffff0000, v186
	v_cvt_pk_bf16_f32 v146, v8, v9
	s_waitcnt vmcnt(40)
	v_pk_fma_f32 v[8:9], v[8:9], v[150:151], v[172:173]
	v_lshlrev_b32_e32 v138, 16, v187
	v_cvt_pk_bf16_f32 v147, v8, v9
	v_and_b32_e32 v139, 0xffff0000, v187
	s_waitcnt vmcnt(39)
	v_lshlrev_b32_e32 v140, 16, v188
	v_and_b32_e32 v141, 0xffff0000, v188
	s_waitcnt vmcnt(38)
	v_lshlrev_b32_e32 v142, 16, v189
	v_and_b32_e32 v143, 0xffff0000, v189
	global_store_dword v[102:103], v99, off
	global_store_dword v[106:107], v97, off
	global_store_dword v[108:109], v131, off
	global_store_dword v[110:111], v174, off
	global_store_dword v[112:113], v175, off
	global_store_dword v[114:115], v176, off
	global_store_dword v[116:117], v177, off
	global_store_dword v[118:119], v144, off
	global_store_dword v[120:121], v145, off
	global_store_dword v[124:125], v146, off
	global_store_dword v[126:127], v147, off
	s_waitcnt vmcnt(48)
	v_pk_fma_f32 v[102:103], v[8:9], v[152:153], v[132:133]
	v_cvt_pk_bf16_f32 v97, v102, v103
	s_waitcnt vmcnt(47)
	v_pk_fma_f32 v[102:103], v[102:103], v[154:155], v[134:135]
	global_store_dword v[122:123], v97, off
	v_cvt_pk_bf16_f32 v97, v102, v103
	s_waitcnt vmcnt(47)
	v_pk_fma_f32 v[102:103], v[102:103], v[158:159], v[136:137]
	global_store_dword v[156:157], v97, off
	v_cvt_pk_bf16_f32 v97, v102, v103
	s_waitcnt vmcnt(47)
	v_pk_fma_f32 v[102:103], v[102:103], v[162:163], v[138:139]
	global_store_dword v[160:161], v97, off
	v_cvt_pk_bf16_f32 v97, v102, v103
	s_waitcnt vmcnt(47)
	v_pk_fma_f32 v[102:103], v[102:103], v[166:167], v[140:141]
	global_store_dword v[164:165], v97, off
	v_cvt_pk_bf16_f32 v97, v102, v103
	s_waitcnt vmcnt(47)
	v_pk_fma_f32 v[8:9], v[102:103], v[168:169], v[142:143]
	global_store_dword v[100:101], v97, off
	v_add_u32_e32 v98, 0x800, v2
	v_lshl_add_u64 v[100:101], v[4:5], 0, s[14:15]
	v_add_co_u32_e32 v102, vcc, 0xfff88000, v100
	v_add_u32_e32 v106, 0xfffff880, v98
	s_nop 0
	v_addc_co_u32_e32 v103, vcc, -1, v101, vcc
	v_ashrrev_i32_e32 v107, 31, v106
	v_lshl_add_u64 v[132:133], v[106:107], 2, s[2:3]
	v_add_co_u32_e32 v106, vcc, 0xfff90000, v100
	v_add_u32_e32 v108, 0xfffff900, v98
	s_nop 0
	v_addc_co_u32_e32 v107, vcc, -1, v101, vcc
	v_ashrrev_i32_e32 v109, 31, v108
	v_lshl_add_u64 v[134:135], v[108:109], 2, s[2:3]
	v_add_co_u32_e32 v108, vcc, 0xfff98000, v100
	v_add_u32_e32 v110, 0xfffff980, v98
	s_nop 0
	v_addc_co_u32_e32 v109, vcc, -1, v101, vcc
	v_ashrrev_i32_e32 v111, 31, v110
	v_lshl_add_u64 v[136:137], v[110:111], 2, s[2:3]
	v_add_co_u32_e32 v110, vcc, 0xfffa0000, v100
	v_add_u32_e32 v112, 0xfffffa00, v98
	s_nop 0
	v_addc_co_u32_e32 v111, vcc, -1, v101, vcc
	v_ashrrev_i32_e32 v113, 31, v112
	v_lshl_add_u64 v[138:139], v[112:113], 2, s[2:3]
	v_add_co_u32_e32 v112, vcc, 0xfffa8000, v100
	v_add_u32_e32 v114, 0xfffffa80, v98
	s_nop 0
	v_addc_co_u32_e32 v113, vcc, -1, v101, vcc
	v_ashrrev_i32_e32 v115, 31, v114
	v_lshl_add_u64 v[140:141], v[114:115], 2, s[2:3]
	v_add_co_u32_e32 v114, vcc, 0xfffb0000, v100
	v_add_u32_e32 v116, 0xfffffb00, v98
	s_nop 0
	v_addc_co_u32_e32 v115, vcc, -1, v101, vcc
	v_ashrrev_i32_e32 v117, 31, v116
	v_lshl_add_u64 v[142:143], v[116:117], 2, s[2:3]
	v_add_co_u32_e32 v116, vcc, 0xfffb8000, v100
	v_add_u32_e32 v118, 0xfffffb80, v98
	s_nop 0
	v_addc_co_u32_e32 v117, vcc, -1, v101, vcc
	v_ashrrev_i32_e32 v119, 31, v118
	v_lshl_add_u64 v[144:145], v[118:119], 2, s[2:3]
	v_add_co_u32_e32 v118, vcc, 0xfffc0000, v100
	v_add_u32_e32 v120, 0xfffffc00, v98
	s_nop 0
	v_addc_co_u32_e32 v119, vcc, -1, v101, vcc
	v_ashrrev_i32_e32 v121, 31, v120
	v_lshl_add_u64 v[146:147], v[120:121], 2, s[2:3]
	v_add_co_u32_e32 v120, vcc, 0xfffc8000, v100
	v_add_u32_e32 v122, 0xfffffc80, v98
	s_nop 0
	v_addc_co_u32_e32 v121, vcc, -1, v101, vcc
	v_ashrrev_i32_e32 v123, 31, v122
	v_lshl_add_u64 v[148:149], v[122:123], 2, s[2:3]
	v_add_co_u32_e32 v124, vcc, 0xfffd0000, v100
	v_add_u32_e32 v122, 0xfffffd00, v98
	s_nop 0
	v_addc_co_u32_e32 v125, vcc, -1, v101, vcc
	v_ashrrev_i32_e32 v123, 31, v122
	v_lshl_add_u64 v[150:151], v[122:123], 2, s[2:3]
	v_add_co_u32_e32 v126, vcc, 0xfffd8000, v100
	v_add_u32_e32 v122, 0xfffffd80, v98
	s_nop 0
	v_addc_co_u32_e32 v127, vcc, -1, v101, vcc
	v_ashrrev_i32_e32 v123, 31, v122
	s_mov_b32 s13, 0xfffe0000
	v_lshl_add_u64 v[152:153], v[122:123], 2, s[2:3]
	v_add_co_u32_e32 v122, vcc, s13, v100
	global_load_dword v97, v[102:103], off
	global_load_dword v131, v[106:107], off
	global_load_dword v175, v[108:109], off
	global_load_dword v177, v[110:111], off
	global_load_dword v178, v[112:113], off
	global_load_dword v179, v[114:115], off
	global_load_dword v180, v[116:117], off
	global_load_dword v181, v[118:119], off
	v_addc_co_u32_e32 v123, vcc, -1, v101, vcc
	s_mov_b32 s13, 0xfffe8000
	global_load_dwordx2 v[132:133], v[132:133], off
	v_add_co_u32_e32 v156, vcc, s13, v100
	s_mov_b32 s13, 0xffff0000
	s_nop 0
	v_addc_co_u32_e32 v157, vcc, -1, v101, vcc
	global_load_dword v182, v[120:121], off
	global_load_dword v183, v[124:125], off
	global_load_dword v184, v[126:127], off
	global_load_dword v185, v[122:123], off
	s_nop 0
	global_load_dwordx2 v[134:135], v[134:135], off
	s_nop 0
	global_load_dwordx2 v[136:137], v[136:137], off
	v_add_co_u32_e32 v160, vcc, s13, v100
	v_add_u32_e32 v154, 0xfffffe00, v98
	global_load_dwordx2 v[138:139], v[138:139], off
	v_add_u32_e32 v158, 0xfffffe80, v98
	v_addc_co_u32_e32 v161, vcc, -1, v101, vcc
	v_add_u32_e32 v162, 0xffffff00, v98
	s_movk_i32 s13, 0x8000
	v_add_u32_e32 v166, 0xffffff80, v98
	v_ashrrev_i32_e32 v155, 31, v154
	v_ashrrev_i32_e32 v159, 31, v158
	global_load_dwordx2 v[140:141], v[140:141], off
	v_ashrrev_i32_e32 v163, 31, v162
	v_add_co_u32_e32 v164, vcc, s13, v100
	v_ashrrev_i32_e32 v167, 31, v166
	v_ashrrev_i32_e32 v99, 31, v98
	v_lshl_add_u64 v[154:155], v[154:155], 2, s[2:3]
	v_lshl_add_u64 v[158:159], v[158:159], 2, s[2:3]
	global_load_dwordx2 v[142:143], v[142:143], off
	v_lshl_add_u64 v[162:163], v[162:163], 2, s[2:3]
	v_addc_co_u32_e32 v165, vcc, -1, v101, vcc
	v_lshl_add_u64 v[166:167], v[166:167], 2, s[2:3]
	s_waitcnt vmcnt(23)
	v_lshl_add_u64 v[168:169], v[98:99], 2, s[2:3]
	global_load_dword v186, v[156:157], off
	global_load_dword v187, v[160:161], off
	s_nop 0
	global_load_dwordx2 v[144:145], v[144:145], off
	s_nop 0
	global_load_dwordx2 v[146:147], v[146:147], off
	s_nop 0
	global_load_dwordx2 v[148:149], v[148:149], off
	s_nop 0
	global_load_dwordx2 v[150:151], v[150:151], off
	global_load_dword v188, v[164:165], off
	global_load_dword v189, v[100:101], off
	s_nop 0
	global_load_dwordx2 v[152:153], v[152:153], off
	s_nop 0
	global_load_dwordx2 v[154:155], v[154:155], off
	s_nop 0
	global_load_dwordx2 v[158:159], v[158:159], off
	s_nop 0
	global_load_dwordx2 v[162:163], v[162:163], off
	s_nop 0
	global_load_dwordx2 v[166:167], v[166:167], off
	s_nop 0
	global_load_dwordx2 v[168:169], v[168:169], off
	v_cvt_pk_bf16_f32 v3, v8, v9
	s_waitcnt vmcnt(63)
	v_lshlrev_b32_e32 v74, 16, v1
	v_and_b32_e32 v75, 0xffff0000, v1
	s_waitcnt vmcnt(62)
	v_lshlrev_b32_e32 v76, 16, v35
	v_and_b32_e32 v77, 0xffff0000, v35
	s_waitcnt vmcnt(61)
	v_lshlrev_b32_e32 v78, 16, v79
	v_and_b32_e32 v79, 0xffff0000, v79
	s_waitcnt vmcnt(60)
	v_lshlrev_b32_e32 v80, 16, v81
	v_and_b32_e32 v81, 0xffff0000, v81
	s_waitcnt vmcnt(55)
	v_pk_fma_f32 v[8:9], v[8:9], v[36:37], v[74:75]
	s_nop 0
	v_cvt_pk_bf16_f32 v1, v8, v9
	v_lshlrev_b32_e32 v36, 16, v82
	v_and_b32_e32 v37, 0xffff0000, v82
	s_waitcnt vmcnt(54)
	v_lshlrev_b32_e32 v74, 16, v86
	v_and_b32_e32 v75, 0xffff0000, v86
	s_waitcnt vmcnt(50)
	v_pk_fma_f32 v[8:9], v[8:9], v[38:39], v[76:77]
	s_nop 0
	v_cvt_pk_bf16_f32 v35, v8, v9
	s_waitcnt vmcnt(49)
	v_pk_fma_f32 v[8:9], v[8:9], v[40:41], v[78:79]
	v_lshlrev_b32_e32 v38, 16, v83
	v_cvt_pk_bf16_f32 v78, v8, v9
	s_waitcnt vmcnt(48)
	v_pk_fma_f32 v[8:9], v[8:9], v[42:43], v[80:81]
	v_and_b32_e32 v39, 0xffff0000, v83
	v_cvt_pk_bf16_f32 v79, v8, v9
	v_lshlrev_b32_e32 v40, 16, v84
	v_and_b32_e32 v41, 0xffff0000, v84
	v_lshlrev_b32_e32 v42, 16, v85
	v_and_b32_e32 v43, 0xffff0000, v85
	v_lshlrev_b32_e32 v76, 16, v87
	v_and_b32_e32 v77, 0xffff0000, v87
	s_waitcnt vmcnt(47)
	v_pk_fma_f32 v[8:9], v[8:9], v[44:45], v[36:37]
	v_lshlrev_b32_e32 v36, 16, v88
	v_cvt_pk_bf16_f32 v80, v8, v9
	v_and_b32_e32 v37, 0xffff0000, v88
	s_waitcnt vmcnt(46)
	v_pk_fma_f32 v[8:9], v[8:9], v[46:47], v[38:39]
	s_nop 0
	v_cvt_pk_bf16_f32 v81, v8, v9
	v_lshlrev_b32_e32 v38, 16, v89
	v_and_b32_e32 v39, 0xffff0000, v89
	s_waitcnt vmcnt(43)
	v_pk_fma_f32 v[8:9], v[8:9], v[48:49], v[40:41]
	s_nop 0
	v_cvt_pk_bf16_f32 v48, v8, v9
	s_waitcnt vmcnt(42)
	v_pk_fma_f32 v[8:9], v[8:9], v[50:51], v[42:43]
	v_lshlrev_b32_e32 v40, 16, v90
	v_cvt_pk_bf16_f32 v49, v8, v9
	s_waitcnt vmcnt(41)
	v_pk_fma_f32 v[8:9], v[8:9], v[52:53], v[74:75]
	v_and_b32_e32 v41, 0xffff0000, v90
	v_cvt_pk_bf16_f32 v50, v8, v9
	s_waitcnt vmcnt(40)
	v_pk_fma_f32 v[8:9], v[8:9], v[54:55], v[76:77]
	v_lshlrev_b32_e32 v42, 16, v91
	v_cvt_pk_bf16_f32 v51, v8, v9
	v_and_b32_e32 v43, 0xffff0000, v91
	s_waitcnt vmcnt(39)
	v_lshlrev_b32_e32 v44, 16, v92
	v_and_b32_e32 v45, 0xffff0000, v92
	s_waitcnt vmcnt(38)
	v_lshlrev_b32_e32 v46, 16, v93
	v_and_b32_e32 v47, 0xffff0000, v93
	global_store_dword v[6:7], v3, off
	global_store_dword v[10:11], v1, off
	global_store_dword v[12:13], v35, off
	global_store_dword v[14:15], v78, off
	global_store_dword v[16:17], v79, off
	global_store_dword v[18:19], v80, off
	global_store_dword v[20:21], v81, off
	global_store_dword v[22:23], v48, off
	global_store_dword v[24:25], v49, off
	global_store_dword v[28:29], v50, off
	global_store_dword v[30:31], v51, off
	s_waitcnt vmcnt(48)
	v_pk_fma_f32 v[6:7], v[8:9], v[56:57], v[36:37]
	v_cvt_pk_bf16_f32 v1, v6, v7
	s_waitcnt vmcnt(47)
	v_pk_fma_f32 v[6:7], v[6:7], v[58:59], v[38:39]
	global_store_dword v[26:27], v1, off
	v_cvt_pk_bf16_f32 v1, v6, v7
	s_waitcnt vmcnt(47)
	v_pk_fma_f32 v[6:7], v[6:7], v[62:63], v[40:41]
	global_store_dword v[60:61], v1, off
	v_cvt_pk_bf16_f32 v1, v6, v7
	s_waitcnt vmcnt(47)
	v_pk_fma_f32 v[6:7], v[6:7], v[66:67], v[42:43]
	global_store_dword v[64:65], v1, off
	v_cvt_pk_bf16_f32 v1, v6, v7
	s_waitcnt vmcnt(47)
	v_pk_fma_f32 v[6:7], v[6:7], v[70:71], v[44:45]
	global_store_dword v[68:69], v1, off
	v_cvt_pk_bf16_f32 v1, v6, v7
	s_waitcnt vmcnt(47)
	v_pk_fma_f32 v[8:9], v[6:7], v[72:73], v[46:47]
	global_store_dword v[4:5], v1, off
	v_cvt_pk_bf16_f32 v99, v8, v9
	s_waitcnt vmcnt(31)
	v_lshlrev_b32_e32 v170, 16, v97
	v_and_b32_e32 v171, 0xffff0000, v97
	s_waitcnt vmcnt(30)
	v_lshlrev_b32_e32 v172, 16, v131
	v_and_b32_e32 v173, 0xffff0000, v131
	s_waitcnt vmcnt(29)
	v_lshlrev_b32_e32 v174, 16, v175
	v_and_b32_e32 v175, 0xffff0000, v175
	s_waitcnt vmcnt(28)
	v_lshlrev_b32_e32 v176, 16, v177
	v_and_b32_e32 v177, 0xffff0000, v177
	s_waitcnt vmcnt(23)
	v_pk_fma_f32 v[8:9], v[8:9], v[132:133], v[170:171]
	s_nop 0
	v_cvt_pk_bf16_f32 v97, v8, v9
	v_lshlrev_b32_e32 v132, 16, v178
	v_and_b32_e32 v133, 0xffff0000, v178
	s_waitcnt vmcnt(22)
	v_lshlrev_b32_e32 v170, 16, v182
	v_and_b32_e32 v171, 0xffff0000, v182
	s_waitcnt vmcnt(18)
	v_pk_fma_f32 v[8:9], v[8:9], v[134:135], v[172:173]
	s_nop 0
	v_cvt_pk_bf16_f32 v131, v8, v9
	s_waitcnt vmcnt(17)
	v_pk_fma_f32 v[8:9], v[8:9], v[136:137], v[174:175]
	v_lshlrev_b32_e32 v134, 16, v179
	v_cvt_pk_bf16_f32 v174, v8, v9
	s_waitcnt vmcnt(16)
	v_pk_fma_f32 v[8:9], v[8:9], v[138:139], v[176:177]
	v_and_b32_e32 v135, 0xffff0000, v179
	v_cvt_pk_bf16_f32 v175, v8, v9
	v_lshlrev_b32_e32 v136, 16, v180
	v_and_b32_e32 v137, 0xffff0000, v180
	v_lshlrev_b32_e32 v138, 16, v181
	v_and_b32_e32 v139, 0xffff0000, v181
	v_lshlrev_b32_e32 v172, 16, v183
	v_and_b32_e32 v173, 0xffff0000, v183
	s_waitcnt vmcnt(15)
	v_pk_fma_f32 v[8:9], v[8:9], v[140:141], v[132:133]
	v_lshlrev_b32_e32 v132, 16, v184
	v_cvt_pk_bf16_f32 v176, v8, v9
	v_and_b32_e32 v133, 0xffff0000, v184
	s_waitcnt vmcnt(14)
	v_pk_fma_f32 v[8:9], v[8:9], v[142:143], v[134:135]
	s_nop 0
	v_cvt_pk_bf16_f32 v177, v8, v9
	v_lshlrev_b32_e32 v134, 16, v185
	v_and_b32_e32 v135, 0xffff0000, v185
	s_waitcnt vmcnt(11)
	v_pk_fma_f32 v[8:9], v[8:9], v[144:145], v[136:137]
	s_nop 0
	v_cvt_pk_bf16_f32 v144, v8, v9
	s_waitcnt vmcnt(10)
	v_pk_fma_f32 v[8:9], v[8:9], v[146:147], v[138:139]
	v_lshlrev_b32_e32 v136, 16, v186
	v_cvt_pk_bf16_f32 v145, v8, v9
	s_waitcnt vmcnt(9)
	v_pk_fma_f32 v[8:9], v[8:9], v[148:149], v[170:171]
	v_and_b32_e32 v137, 0xffff0000, v186
	v_cvt_pk_bf16_f32 v146, v8, v9
	s_waitcnt vmcnt(8)
	v_pk_fma_f32 v[8:9], v[8:9], v[150:151], v[172:173]
	v_lshlrev_b32_e32 v138, 16, v187
	v_cvt_pk_bf16_f32 v147, v8, v9
	v_and_b32_e32 v139, 0xffff0000, v187
	s_waitcnt vmcnt(7)
	v_lshlrev_b32_e32 v140, 16, v188
	v_and_b32_e32 v141, 0xffff0000, v188
	s_waitcnt vmcnt(6)
	v_lshlrev_b32_e32 v142, 16, v189
	v_and_b32_e32 v143, 0xffff0000, v189
	global_store_dword v[102:103], v99, off
	global_store_dword v[106:107], v97, off
	global_store_dword v[108:109], v131, off
	global_store_dword v[110:111], v174, off
	global_store_dword v[112:113], v175, off
	global_store_dword v[114:115], v176, off
	global_store_dword v[116:117], v177, off
	global_store_dword v[118:119], v144, off
	global_store_dword v[120:121], v145, off
	global_store_dword v[124:125], v146, off
	global_store_dword v[126:127], v147, off
	s_waitcnt vmcnt(16)
	v_pk_fma_f32 v[102:103], v[8:9], v[152:153], v[132:133]
	v_cvt_pk_bf16_f32 v97, v102, v103
	s_waitcnt vmcnt(15)
	v_pk_fma_f32 v[102:103], v[102:103], v[154:155], v[134:135]
	global_store_dword v[122:123], v97, off
	v_cvt_pk_bf16_f32 v97, v102, v103
	s_waitcnt vmcnt(15)
	v_pk_fma_f32 v[102:103], v[102:103], v[158:159], v[136:137]
	global_store_dword v[156:157], v97, off
	v_cvt_pk_bf16_f32 v97, v102, v103
	s_waitcnt vmcnt(15)
	v_pk_fma_f32 v[102:103], v[102:103], v[162:163], v[138:139]
	global_store_dword v[160:161], v97, off
	v_cvt_pk_bf16_f32 v97, v102, v103
	s_waitcnt vmcnt(15)
	v_pk_fma_f32 v[102:103], v[102:103], v[166:167], v[140:141]
	global_store_dword v[164:165], v97, off
	v_cvt_pk_bf16_f32 v97, v102, v103
	s_waitcnt vmcnt(15)
	v_pk_fma_f32 v[8:9], v[102:103], v[168:169], v[142:143]
	global_store_dword v[100:101], v97, off
	v_and_b32_e32 v2, 0x1fc0, v32
	v_ashrrev_i32_e32 v1, 31, v0
	v_lshl_add_u64 v[0:1], v[0:1], 0, s[54:55]
	v_lshlrev_b32_e32 v3, 10, v32
	v_lshrrev_b32_e32 v2, 4, v2
	s_mov_b32 s12, 0xfc00
	v_lshlrev_b64 v[0:1], 16, v[0:1]
	v_and_or_b32 v208, v3, s12, v2
	v_add_u32_e32 v32, s10, v32
	s_mov_b32 s12, 0x1ffff
	v_lshl_add_u64 v[0:1], s[4:5], 0, v[0:1]
	v_cmp_lt_i32_e32 vcc, s12, v32
	v_lshl_add_u64 v[0:1], v[0:1], 0, v[208:209]
	v_add_u32_e32 v33, s11, v33
	s_or_b64 s[8:9], vcc, s[8:9]
	v_add_u16_e32 v34, s10, v34
	global_store_dword v[0:1], v8, off
	global_store_dword v[0:1], v9, off offset:512
	s_andn2_b64 exec, exec, s[8:9]
	s_cbranch_execnz .LBB0_406
